# gate/up SwiGLU epilogue: exp-argument multiplies and +1 adds packed (v_pk_mul_f32 / v_pk_add_f32), same f32 math
# baseline (speedup 1.0000x reference)
.LBB0_1100:
	s_mov_b32 s100, 0xbfb8aa3b
	s_mov_b32 s101, 1.0
	v_lshl_add_u32 v150, s3, 10, v148
	ds_read2_b32 v[152:153], v150 offset1:16
	v_lshl_or_b32 v140, s2, 7, v147
	s_lshl_b32 s2, s24, 8
	v_ashrrev_i32_e32 v141, 31, v140
	s_andn2_b64 vcc, exec, s[4:5]
	s_waitcnt lgkmcnt(0)
	v_pk_mul_f32 v[126:127], v[126:127], v[152:153] op_sel_hi:[1,0]
	v_pk_mul_f32 v[122:123], v[122:123], v[152:153] op_sel_hi:[1,0]
	v_mul_f32_e32 v151, 0xbfb8aa3b, v126
	v_exp_f32_e32 v151, v151
	v_pk_mul_f32 v[124:125], v[124:125], v[152:153] op_sel_hi:[1,0]
	v_pk_mul_f32 v[118:119], v[118:119], v[152:153] op_sel_hi:[1,0]
	v_pk_mul_f32 v[114:115], v[114:115], v[152:153] op_sel_hi:[1,0]
	v_add_f32_e32 v151, 1.0, v151
	v_rcp_f32_e32 v154, v151
	v_mul_f32_e32 v151, 0xbfb8aa3b, v127
	v_exp_f32_e32 v151, v151
	v_pk_mul_f32 v[116:117], v[116:117], v[152:153] op_sel_hi:[1,0]
	v_add_f32_e32 v151, 1.0, v151
	v_rcp_f32_e32 v155, v151
	s_nop 0
	v_pk_mul_f32 v[126:127], v[126:127], v[154:155]
	s_nop 0
	v_pk_mul_f32 v[122:123], v[122:123], v[126:127]
	v_pk_mul_f32 v[126:127], v[128:129], v[152:153] op_sel_hi:[1,0]
	s_nop 0
	v_pk_mul_f32 v[128:129], v[126:127], s[100:101] op_sel_hi:[1,0]
	v_exp_f32_e32 v128, v128
	v_exp_f32_e32 v129, v129
	s_nop 0
	v_pk_add_f32 v[128:129], v[128:129], s[100:101] op_sel:[0,1]
	v_rcp_f32_e32 v128, v128
	v_rcp_f32_e32 v129, v129
	s_nop 0
	v_pk_mul_f32 v[126:127], v[126:127], v[128:129]
	s_nop 0
	v_pk_mul_f32 v[124:125], v[124:125], v[126:127]
	v_pk_mul_f32 v[126:127], v[118:119], s[100:101] op_sel_hi:[1,0]
	v_exp_f32_e32 v126, v126
	v_exp_f32_e32 v127, v127
	s_nop 0
	v_pk_add_f32 v[126:127], v[126:127], s[100:101] op_sel:[0,1]
	v_rcp_f32_e32 v126, v126
	v_rcp_f32_e32 v127, v127
	s_nop 0
	v_pk_mul_f32 v[118:119], v[118:119], v[126:127]
	s_nop 0
	v_pk_mul_f32 v[114:115], v[114:115], v[118:119]
	v_pk_mul_f32 v[118:119], v[120:121], v[152:153] op_sel_hi:[1,0]
	s_nop 0
	v_pk_mul_f32 v[120:121], v[118:119], s[100:101] op_sel_hi:[1,0]
	v_exp_f32_e32 v120, v120
	v_exp_f32_e32 v121, v121
	s_nop 0
	v_pk_add_f32 v[120:121], v[120:121], s[100:101] op_sel:[0,1]
	v_rcp_f32_e32 v120, v120
	v_rcp_f32_e32 v121, v121
	s_nop 0
	v_pk_mul_f32 v[118:119], v[118:119], v[120:121]
	s_nop 0
	v_pk_mul_f32 v[116:117], v[116:117], v[118:119]
	v_cvt_pk_bf16_f32 v120, v122, v123
	v_cvt_pk_bf16_f32 v122, v114, v115
	v_add_u32_e32 v118, s2, v142
	v_mov_b64_e32 v[114:115], s[12:13]
	v_cvt_pk_bf16_f32 v121, v124, v125
	v_cvt_pk_bf16_f32 v123, v116, v117
	v_mad_i64_i32 v[124:125], s[24:25], v118, s63, v[114:115]
	v_lshlrev_b64 v[116:117], 1, v[140:141]
	v_lshl_add_u64 v[124:125], v[124:125], 0, v[116:117]
	global_store_dwordx4 v[124:125], v[120:123], off
	s_nop 1
	v_mov_b32_e32 v120, v153
	v_pk_mul_f32 v[110:111], v[110:111], v[120:121] op_sel_hi:[1,0]
	v_pk_mul_f32 v[106:107], v[106:107], v[120:121] op_sel_hi:[1,0]
	v_mul_f32_e32 v119, 0xbfb8aa3b, v110
	v_exp_f32_e32 v119, v119
	v_pk_mul_f32 v[108:109], v[108:109], v[120:121] op_sel_hi:[1,0]
	v_pk_mul_f32 v[102:103], v[102:103], v[120:121] op_sel_hi:[1,0]
	v_pk_mul_f32 v[98:99], v[98:99], v[120:121] op_sel_hi:[1,0]
	v_add_f32_e32 v119, 1.0, v119
	v_rcp_f32_e32 v122, v119
	v_mul_f32_e32 v119, 0xbfb8aa3b, v111
	v_exp_f32_e32 v119, v119
	v_pk_mul_f32 v[100:101], v[100:101], v[120:121] op_sel_hi:[1,0]
	v_add_f32_e32 v119, 1.0, v119
	v_rcp_f32_e32 v123, v119
	s_nop 0
	v_pk_mul_f32 v[110:111], v[110:111], v[122:123]
	s_nop 0
	v_pk_mul_f32 v[106:107], v[106:107], v[110:111]
	v_pk_mul_f32 v[110:111], v[112:113], v[120:121] op_sel_hi:[1,0]
	s_nop 0
	v_pk_mul_f32 v[112:113], v[110:111], s[100:101] op_sel_hi:[1,0]
	v_exp_f32_e32 v112, v112
	v_exp_f32_e32 v113, v113
	s_nop 0
	v_pk_add_f32 v[112:113], v[112:113], s[100:101] op_sel:[0,1]
	v_rcp_f32_e32 v112, v112
	v_rcp_f32_e32 v113, v113
	s_nop 0
	v_pk_mul_f32 v[110:111], v[110:111], v[112:113]
	s_nop 0
	v_pk_mul_f32 v[108:109], v[108:109], v[110:111]
	v_pk_mul_f32 v[110:111], v[102:103], s[100:101] op_sel_hi:[1,0]
	v_exp_f32_e32 v110, v110
	v_exp_f32_e32 v111, v111
	s_nop 0
	v_pk_add_f32 v[110:111], v[110:111], s[100:101] op_sel:[0,1]
	v_rcp_f32_e32 v110, v110
	v_rcp_f32_e32 v111, v111
	s_nop 0
	v_pk_mul_f32 v[102:103], v[102:103], v[110:111]
	s_nop 0
	v_pk_mul_f32 v[102:103], v[98:99], v[102:103]
	v_pk_mul_f32 v[98:99], v[104:105], v[120:121] op_sel_hi:[1,0]
	s_nop 0
	v_pk_mul_f32 v[104:105], v[98:99], s[100:101] op_sel_hi:[1,0]
	v_exp_f32_e32 v104, v104
	v_exp_f32_e32 v105, v105
	s_nop 0
	v_pk_add_f32 v[104:105], v[104:105], s[100:101] op_sel:[0,1]
	v_rcp_f32_e32 v104, v104
	v_rcp_f32_e32 v105, v105
	s_nop 0
	v_pk_mul_f32 v[98:99], v[98:99], v[104:105]
	s_nop 0
	v_pk_mul_f32 v[104:105], v[100:101], v[98:99]
	v_cvt_pk_bf16_f32 v100, v102, v103
	v_add_u32_e32 v102, s2, v144
	v_mad_i64_i32 v[102:103], s[24:25], v102, s63, v[114:115]
	v_cvt_pk_bf16_f32 v98, v106, v107
	v_cvt_pk_bf16_f32 v99, v108, v109
	v_cvt_pk_bf16_f32 v101, v104, v105
	v_lshl_add_u64 v[102:103], v[102:103], 0, v[116:117]
	global_store_dwordx4 v[102:103], v[98:101], off
	ds_read2_b32 v[98:99], v150 offset0:32 offset1:48
	s_waitcnt lgkmcnt(0)
	v_pk_mul_f32 v[94:95], v[94:95], v[98:99] op_sel_hi:[1,0]
	s_nop 0
	v_pk_mul_f32 v[100:101], v[94:95], s[100:101] op_sel_hi:[1,0]
	v_exp_f32_e32 v100, v100
	v_exp_f32_e32 v101, v101
	v_pk_mul_f32 v[90:91], v[90:91], v[98:99] op_sel_hi:[1,0]
	v_pk_mul_f32 v[92:93], v[92:93], v[98:99] op_sel_hi:[1,0]
	v_pk_add_f32 v[100:101], v[100:101], s[100:101] op_sel:[0,1]
	v_rcp_f32_e32 v100, v100
	v_rcp_f32_e32 v101, v101
	v_pk_mul_f32 v[86:87], v[86:87], v[98:99] op_sel_hi:[1,0]
	v_pk_mul_f32 v[82:83], v[82:83], v[98:99] op_sel_hi:[1,0]
	v_pk_mul_f32 v[84:85], v[84:85], v[98:99] op_sel_hi:[1,0]
	v_pk_mul_f32 v[94:95], v[94:95], v[100:101]
	s_nop 0
	v_pk_mul_f32 v[90:91], v[90:91], v[94:95]
	v_pk_mul_f32 v[94:95], v[96:97], v[98:99] op_sel_hi:[1,0]
	s_nop 0
	v_pk_mul_f32 v[96:97], v[94:95], s[100:101] op_sel_hi:[1,0]
	v_exp_f32_e32 v96, v96
	v_exp_f32_e32 v97, v97
	s_nop 0
	v_pk_add_f32 v[96:97], v[96:97], s[100:101] op_sel:[0,1]
	v_rcp_f32_e32 v96, v96
	v_rcp_f32_e32 v97, v97
	s_nop 0
	v_pk_mul_f32 v[94:95], v[94:95], v[96:97]
	s_nop 0
	v_pk_mul_f32 v[92:93], v[92:93], v[94:95]
	v_pk_mul_f32 v[94:95], v[86:87], s[100:101] op_sel_hi:[1,0]
	v_exp_f32_e32 v94, v94
	v_exp_f32_e32 v95, v95
	s_nop 0
	v_pk_add_f32 v[94:95], v[94:95], s[100:101] op_sel:[0,1]
	v_rcp_f32_e32 v94, v94
	v_rcp_f32_e32 v95, v95
	s_nop 0
	v_pk_mul_f32 v[86:87], v[86:87], v[94:95]
	s_nop 0
	v_pk_mul_f32 v[86:87], v[82:83], v[86:87]
	v_pk_mul_f32 v[82:83], v[88:89], v[98:99] op_sel_hi:[1,0]
	s_nop 0
	v_pk_mul_f32 v[88:89], v[82:83], s[100:101] op_sel_hi:[1,0]
	v_exp_f32_e32 v88, v88
	v_exp_f32_e32 v89, v89
	s_nop 0
	v_pk_add_f32 v[88:89], v[88:89], s[100:101] op_sel:[0,1]
	v_rcp_f32_e32 v88, v88
	v_rcp_f32_e32 v89, v89
	s_nop 0
	v_pk_mul_f32 v[82:83], v[82:83], v[88:89]
	s_nop 0
	v_pk_mul_f32 v[88:89], v[84:85], v[82:83]
	v_cvt_pk_bf16_f32 v84, v86, v87
	v_add_u32_e32 v86, s2, v145
	v_mad_i64_i32 v[86:87], s[24:25], v86, s63, v[114:115]
	v_cvt_pk_bf16_f32 v82, v90, v91
	v_cvt_pk_bf16_f32 v83, v92, v93
	v_cvt_pk_bf16_f32 v85, v88, v89
	v_lshl_add_u64 v[86:87], v[86:87], 0, v[116:117]
	global_store_dwordx4 v[86:87], v[82:85], off
	s_mov_b64 s[24:25], -1
	s_nop 0
	v_mov_b32_e32 v82, v99
	v_pk_mul_f32 v[78:79], v[78:79], v[82:83] op_sel_hi:[1,0]
	s_nop 0
	v_mul_f32_e32 v83, 0xbfb8aa3b, v78
	v_exp_f32_e32 v83, v83
	s_nop 0
	v_add_f32_e32 v83, 1.0, v83
	v_rcp_f32_e32 v84, v83
	v_mul_f32_e32 v83, 0xbfb8aa3b, v79
	v_exp_f32_e32 v83, v83
	s_nop 0
	v_add_f32_e32 v83, 1.0, v83
	v_rcp_f32_e32 v85, v83
	v_pk_mul_f32 v[74:75], v[74:75], v[82:83] op_sel_hi:[1,0]
	v_pk_mul_f32 v[76:77], v[76:77], v[82:83] op_sel_hi:[1,0]
	v_pk_mul_f32 v[70:71], v[70:71], v[82:83] op_sel_hi:[1,0]
	v_pk_mul_f32 v[78:79], v[78:79], v[84:85]
	v_pk_mul_f32 v[66:67], v[66:67], v[82:83] op_sel_hi:[1,0]
	v_pk_mul_f32 v[74:75], v[74:75], v[78:79]
	v_pk_mul_f32 v[78:79], v[80:81], v[82:83] op_sel_hi:[1,0]
	v_pk_mul_f32 v[68:69], v[68:69], v[82:83] op_sel_hi:[1,0]
	v_pk_mul_f32 v[80:81], v[78:79], s[100:101] op_sel_hi:[1,0]
	v_exp_f32_e32 v80, v80
	v_exp_f32_e32 v81, v81
	s_nop 0
	v_pk_add_f32 v[80:81], v[80:81], s[100:101] op_sel:[0,1]
	v_rcp_f32_e32 v80, v80
	v_rcp_f32_e32 v81, v81
	s_nop 0
	v_pk_mul_f32 v[78:79], v[78:79], v[80:81]
	s_nop 0
	v_pk_mul_f32 v[76:77], v[76:77], v[78:79]
	v_pk_mul_f32 v[78:79], v[70:71], s[100:101] op_sel_hi:[1,0]
	v_exp_f32_e32 v78, v78
	v_exp_f32_e32 v79, v79
	s_nop 0
	v_pk_add_f32 v[78:79], v[78:79], s[100:101] op_sel:[0,1]
	v_rcp_f32_e32 v78, v78
	v_rcp_f32_e32 v79, v79
	s_nop 0
	v_pk_mul_f32 v[70:71], v[70:71], v[78:79]
	s_nop 0
	v_pk_mul_f32 v[70:71], v[66:67], v[70:71]
	v_pk_mul_f32 v[66:67], v[72:73], v[82:83] op_sel_hi:[1,0]
	s_nop 0
	v_pk_mul_f32 v[72:73], v[66:67], s[100:101] op_sel_hi:[1,0]
	v_exp_f32_e32 v72, v72
	v_exp_f32_e32 v73, v73
	s_nop 0
	v_pk_add_f32 v[72:73], v[72:73], s[100:101] op_sel:[0,1]
	v_rcp_f32_e32 v72, v72
	v_rcp_f32_e32 v73, v73
	s_nop 0
	v_pk_mul_f32 v[66:67], v[66:67], v[72:73]
	s_nop 0
	v_pk_mul_f32 v[72:73], v[68:69], v[66:67]
	v_cvt_pk_bf16_f32 v68, v70, v71
	v_add_u32_e32 v70, s2, v146
	v_mad_i64_i32 v[70:71], s[2:3], v70, s63, v[114:115]
	v_cvt_pk_bf16_f32 v66, v74, v75
	v_cvt_pk_bf16_f32 v67, v76, v77
	v_cvt_pk_bf16_f32 v69, v72, v73
	v_lshl_add_u64 v[70:71], v[70:71], 0, v[116:117]
	global_store_dwordx4 v[70:71], v[66:69], off
	ds_read2_b32 v[66:67], v150 offset0:128 offset1:144
	s_waitcnt lgkmcnt(0)
	v_pk_mul_f32 v[62:63], v[62:63], v[66:67] op_sel_hi:[1,0]
	s_nop 0
	v_pk_mul_f32 v[68:69], v[62:63], s[100:101] op_sel_hi:[1,0]
	v_exp_f32_e32 v68, v68
	v_exp_f32_e32 v69, v69
	v_pk_mul_f32 v[58:59], v[58:59], v[66:67] op_sel_hi:[1,0]
	v_pk_mul_f32 v[60:61], v[60:61], v[66:67] op_sel_hi:[1,0]
	v_pk_add_f32 v[68:69], v[68:69], s[100:101] op_sel:[0,1]
	v_rcp_f32_e32 v68, v68
	v_rcp_f32_e32 v69, v69
	v_pk_mul_f32 v[54:55], v[54:55], v[66:67] op_sel_hi:[1,0]
	v_pk_mul_f32 v[50:51], v[50:51], v[66:67] op_sel_hi:[1,0]
	v_pk_mul_f32 v[52:53], v[52:53], v[66:67] op_sel_hi:[1,0]
	v_pk_mul_f32 v[62:63], v[62:63], v[68:69]
	s_nop 0
	v_pk_mul_f32 v[58:59], v[58:59], v[62:63]
	v_pk_mul_f32 v[62:63], v[64:65], v[66:67] op_sel_hi:[1,0]
	s_nop 0
	v_pk_mul_f32 v[64:65], v[62:63], s[100:101] op_sel_hi:[1,0]
	v_exp_f32_e32 v64, v64
	v_exp_f32_e32 v65, v65
	s_nop 0
	v_pk_add_f32 v[64:65], v[64:65], s[100:101] op_sel:[0,1]
	v_rcp_f32_e32 v64, v64
	v_rcp_f32_e32 v65, v65
	s_nop 0
	v_pk_mul_f32 v[62:63], v[62:63], v[64:65]
	s_nop 0
	v_pk_mul_f32 v[60:61], v[60:61], v[62:63]
	v_pk_mul_f32 v[62:63], v[54:55], s[100:101] op_sel_hi:[1,0]
	v_exp_f32_e32 v62, v62
	v_exp_f32_e32 v63, v63
	s_nop 0
	v_pk_add_f32 v[62:63], v[62:63], s[100:101] op_sel:[0,1]
	v_rcp_f32_e32 v62, v62
	v_rcp_f32_e32 v63, v63
	s_nop 0
	v_pk_mul_f32 v[54:55], v[54:55], v[62:63]
	s_nop 0
	v_pk_mul_f32 v[54:55], v[50:51], v[54:55]
	v_pk_mul_f32 v[50:51], v[56:57], v[66:67] op_sel_hi:[1,0]
	s_nop 0
	v_pk_mul_f32 v[56:57], v[50:51], s[100:101] op_sel_hi:[1,0]
	v_exp_f32_e32 v56, v56
	v_exp_f32_e32 v57, v57
	s_nop 0
	v_pk_add_f32 v[56:57], v[56:57], s[100:101] op_sel:[0,1]
	v_rcp_f32_e32 v56, v56
	v_rcp_f32_e32 v57, v57
	s_nop 0
	v_pk_mul_f32 v[50:51], v[50:51], v[56:57]
	s_nop 0
	v_pk_mul_f32 v[56:57], v[52:53], v[50:51]
	v_cvt_pk_bf16_f32 v52, v54, v55
	v_add_u32_e32 v54, 0x80, v118
	v_mad_i64_i32 v[54:55], s[2:3], v54, s63, v[114:115]
	v_cvt_pk_bf16_f32 v50, v58, v59
	v_cvt_pk_bf16_f32 v51, v60, v61
	v_cvt_pk_bf16_f32 v53, v56, v57
	v_lshl_add_u64 v[54:55], v[54:55], 0, v[116:117]
	global_store_dwordx4 v[54:55], v[50:53], off
	s_nop 1
	v_mov_b32_e32 v50, v67
	v_pk_mul_f32 v[46:47], v[46:47], v[50:51] op_sel_hi:[1,0]
	s_nop 0
	v_mul_f32_e32 v51, 0xbfb8aa3b, v46
	v_exp_f32_e32 v51, v51
	s_nop 0
	v_add_f32_e32 v51, 1.0, v51
	v_rcp_f32_e32 v52, v51
	v_mul_f32_e32 v51, 0xbfb8aa3b, v47
	v_exp_f32_e32 v51, v51
	s_nop 0
	v_add_f32_e32 v51, 1.0, v51
	v_rcp_f32_e32 v53, v51
	v_pk_mul_f32 v[42:43], v[42:43], v[50:51] op_sel_hi:[1,0]
	v_pk_mul_f32 v[44:45], v[44:45], v[50:51] op_sel_hi:[1,0]
	v_pk_mul_f32 v[38:39], v[38:39], v[50:51] op_sel_hi:[1,0]
	v_pk_mul_f32 v[46:47], v[46:47], v[52:53]
	v_pk_mul_f32 v[34:35], v[34:35], v[50:51] op_sel_hi:[1,0]
	v_pk_mul_f32 v[42:43], v[42:43], v[46:47]
	v_pk_mul_f32 v[46:47], v[48:49], v[50:51] op_sel_hi:[1,0]
	v_pk_mul_f32 v[36:37], v[36:37], v[50:51] op_sel_hi:[1,0]
	v_pk_mul_f32 v[48:49], v[46:47], s[100:101] op_sel_hi:[1,0]
	v_exp_f32_e32 v48, v48
	v_exp_f32_e32 v49, v49
	s_nop 0
	v_pk_add_f32 v[48:49], v[48:49], s[100:101] op_sel:[0,1]
	v_rcp_f32_e32 v48, v48
	v_rcp_f32_e32 v49, v49
	s_nop 0
	v_pk_mul_f32 v[46:47], v[46:47], v[48:49]
	s_nop 0
	v_pk_mul_f32 v[44:45], v[44:45], v[46:47]
	v_pk_mul_f32 v[46:47], v[38:39], s[100:101] op_sel_hi:[1,0]
	v_exp_f32_e32 v46, v46
	v_exp_f32_e32 v47, v47
	s_nop 0
	v_pk_add_f32 v[46:47], v[46:47], s[100:101] op_sel:[0,1]
	v_rcp_f32_e32 v46, v46
	v_rcp_f32_e32 v47, v47
	s_nop 0
	v_pk_mul_f32 v[38:39], v[38:39], v[46:47]
	s_nop 0
	v_pk_mul_f32 v[38:39], v[34:35], v[38:39]
	v_pk_mul_f32 v[34:35], v[40:41], v[50:51] op_sel_hi:[1,0]
	s_nop 0
	v_pk_mul_f32 v[40:41], v[34:35], s[100:101] op_sel_hi:[1,0]
	v_exp_f32_e32 v40, v40
	v_exp_f32_e32 v41, v41
	s_nop 0
	v_pk_add_f32 v[40:41], v[40:41], s[100:101] op_sel:[0,1]
	v_rcp_f32_e32 v40, v40
	v_rcp_f32_e32 v41, v41
	s_nop 0
	v_pk_mul_f32 v[34:35], v[34:35], v[40:41]
	s_nop 0
	v_pk_mul_f32 v[40:41], v[36:37], v[34:35]
	v_cvt_pk_bf16_f32 v36, v38, v39
	v_add_u32_e32 v38, 0x90, v118
	v_mad_i64_i32 v[38:39], s[2:3], v38, s63, v[114:115]
	v_cvt_pk_bf16_f32 v34, v42, v43
	v_cvt_pk_bf16_f32 v35, v44, v45
	v_cvt_pk_bf16_f32 v37, v40, v41
	v_lshl_add_u64 v[38:39], v[38:39], 0, v[116:117]
	global_store_dwordx4 v[38:39], v[34:37], off
	ds_read2_b32 v[34:35], v150 offset0:160 offset1:176
	s_waitcnt lgkmcnt(0)
	v_pk_mul_f32 v[30:31], v[30:31], v[34:35] op_sel_hi:[1,0]
	s_nop 0
	v_pk_mul_f32 v[36:37], v[30:31], s[100:101] op_sel_hi:[1,0]
	v_exp_f32_e32 v36, v36
	v_exp_f32_e32 v37, v37
	v_pk_mul_f32 v[26:27], v[26:27], v[34:35] op_sel_hi:[1,0]
	v_pk_mul_f32 v[28:29], v[28:29], v[34:35] op_sel_hi:[1,0]
	v_pk_add_f32 v[36:37], v[36:37], s[100:101] op_sel:[0,1]
	v_rcp_f32_e32 v36, v36
	v_rcp_f32_e32 v37, v37
	v_pk_mul_f32 v[22:23], v[22:23], v[34:35] op_sel_hi:[1,0]
	v_pk_mul_f32 v[18:19], v[18:19], v[34:35] op_sel_hi:[1,0]
	v_pk_mul_f32 v[20:21], v[20:21], v[34:35] op_sel_hi:[1,0]
	v_pk_mul_f32 v[30:31], v[30:31], v[36:37]
	s_nop 0
	v_pk_mul_f32 v[26:27], v[26:27], v[30:31]
	v_pk_mul_f32 v[30:31], v[32:33], v[34:35] op_sel_hi:[1,0]
	s_nop 0
	v_pk_mul_f32 v[32:33], v[30:31], s[100:101] op_sel_hi:[1,0]
	v_exp_f32_e32 v32, v32
	v_exp_f32_e32 v33, v33
	s_nop 0
	v_pk_add_f32 v[32:33], v[32:33], s[100:101] op_sel:[0,1]
	v_rcp_f32_e32 v32, v32
	v_rcp_f32_e32 v33, v33
	s_nop 0
	v_pk_mul_f32 v[30:31], v[30:31], v[32:33]
	s_nop 0
	v_pk_mul_f32 v[28:29], v[28:29], v[30:31]
	v_pk_mul_f32 v[30:31], v[22:23], s[100:101] op_sel_hi:[1,0]
	v_exp_f32_e32 v30, v30
	v_exp_f32_e32 v31, v31
	s_nop 0
	v_pk_add_f32 v[30:31], v[30:31], s[100:101] op_sel:[0,1]
	v_rcp_f32_e32 v30, v30
	v_rcp_f32_e32 v31, v31
	s_nop 0
	v_pk_mul_f32 v[22:23], v[22:23], v[30:31]
	s_nop 0
	v_pk_mul_f32 v[22:23], v[18:19], v[22:23]
	v_pk_mul_f32 v[18:19], v[24:25], v[34:35] op_sel_hi:[1,0]
	s_nop 0
	v_pk_mul_f32 v[24:25], v[18:19], s[100:101] op_sel_hi:[1,0]
	v_exp_f32_e32 v24, v24
	v_exp_f32_e32 v25, v25
	s_nop 0
	v_pk_add_f32 v[24:25], v[24:25], s[100:101] op_sel:[0,1]
	v_rcp_f32_e32 v24, v24
	v_rcp_f32_e32 v25, v25
	s_nop 0
	v_pk_mul_f32 v[18:19], v[18:19], v[24:25]
	s_nop 0
	v_pk_mul_f32 v[24:25], v[20:21], v[18:19]
	v_cvt_pk_bf16_f32 v20, v22, v23
	v_add_u32_e32 v22, 0xa0, v118
	v_mad_i64_i32 v[22:23], s[2:3], v22, s63, v[114:115]
	v_cvt_pk_bf16_f32 v18, v26, v27
	v_cvt_pk_bf16_f32 v19, v28, v29
	v_cvt_pk_bf16_f32 v21, v24, v25
	v_lshl_add_u64 v[22:23], v[22:23], 0, v[116:117]
	global_store_dwordx4 v[22:23], v[18:21], off
	s_nop 1
	v_mov_b32_e32 v18, v35
	v_pk_mul_f32 v[14:15], v[14:15], v[18:19] op_sel_hi:[1,0]
	s_nop 0
	v_mul_f32_e32 v19, 0xbfb8aa3b, v14
	v_exp_f32_e32 v19, v19
	s_nop 0
	v_add_f32_e32 v19, 1.0, v19
	v_rcp_f32_e32 v20, v19
	v_mul_f32_e32 v19, 0xbfb8aa3b, v15
	v_exp_f32_e32 v19, v19
	s_nop 0
	v_add_f32_e32 v19, 1.0, v19
	v_rcp_f32_e32 v21, v19
	v_pk_mul_f32 v[10:11], v[10:11], v[18:19] op_sel_hi:[1,0]
	v_pk_mul_f32 v[12:13], v[12:13], v[18:19] op_sel_hi:[1,0]
	v_pk_mul_f32 v[6:7], v[6:7], v[18:19] op_sel_hi:[1,0]
	v_pk_mul_f32 v[14:15], v[14:15], v[20:21]
	v_pk_mul_f32 v[2:3], v[2:3], v[18:19] op_sel_hi:[1,0]
	v_pk_mul_f32 v[10:11], v[10:11], v[14:15]
	v_pk_mul_f32 v[14:15], v[16:17], v[18:19] op_sel_hi:[1,0]
	v_pk_mul_f32 v[4:5], v[4:5], v[18:19] op_sel_hi:[1,0]
	v_pk_mul_f32 v[16:17], v[14:15], s[100:101] op_sel_hi:[1,0]
	v_exp_f32_e32 v16, v16
	v_exp_f32_e32 v17, v17
	s_nop 0
	v_pk_add_f32 v[16:17], v[16:17], s[100:101] op_sel:[0,1]
	v_rcp_f32_e32 v16, v16
	v_rcp_f32_e32 v17, v17
	s_nop 0
	v_pk_mul_f32 v[14:15], v[14:15], v[16:17]
	s_nop 0
	v_pk_mul_f32 v[12:13], v[12:13], v[14:15]
	v_pk_mul_f32 v[14:15], v[6:7], s[100:101] op_sel_hi:[1,0]
	v_exp_f32_e32 v14, v14
	v_exp_f32_e32 v15, v15
	s_nop 0
	v_pk_add_f32 v[14:15], v[14:15], s[100:101] op_sel:[0,1]
	v_rcp_f32_e32 v14, v14
	v_rcp_f32_e32 v15, v15
	s_nop 0
	v_pk_mul_f32 v[6:7], v[6:7], v[14:15]
	s_nop 0
	v_pk_mul_f32 v[6:7], v[2:3], v[6:7]
	v_pk_mul_f32 v[2:3], v[8:9], v[18:19] op_sel_hi:[1,0]
	s_nop 0
	v_pk_mul_f32 v[8:9], v[2:3], s[100:101] op_sel_hi:[1,0]
	v_exp_f32_e32 v8, v8
	v_exp_f32_e32 v9, v9
	s_nop 0
	v_pk_add_f32 v[8:9], v[8:9], s[100:101] op_sel:[0,1]
	v_rcp_f32_e32 v8, v8
	v_rcp_f32_e32 v9, v9
	s_nop 0
	v_pk_mul_f32 v[2:3], v[2:3], v[8:9]
	s_nop 0
	v_pk_mul_f32 v[8:9], v[4:5], v[2:3]
	v_cvt_pk_bf16_f32 v4, v6, v7
	v_add_u32_e32 v6, 0xb0, v118
	v_mad_i64_i32 v[6:7], s[2:3], v6, s63, v[114:115]
	v_cvt_pk_bf16_f32 v2, v10, v11
	v_cvt_pk_bf16_f32 v3, v12, v13
	v_cvt_pk_bf16_f32 v5, v8, v9
	v_lshl_add_u64 v[6:7], v[6:7], 0, v[116:117]
	global_store_dwordx4 v[6:7], v[2:5], off
	s_cbranch_vccnz .LBB0_1093
	s_andn2_b64 vcc, exec, s[8:9]
	s_cbranch_vccnz .LBB0_1092
	s_barrier
	s_branch .LBB0_1092
